# P7c: per-token reduction deferred and interleaved into the next token's LDS-DMA gather chunks (separate accumulator sets)
# speedup vs baseline: 1.0196x; 1.0101x over previous
; #define P7C_LOADA(R0, R1, C, S, X, t) do { const int tt_ = (t) < NT_TOK ? (t) : NT_TOK - 1; const unsigned char* rp_ = rp0 + (size_t)tt_ * 256; R0 = *(const v4u*)rp_; R1 = *(const v4u*)(rp_ + 16); \
;             C = *(const v4u*)(cp0 + (size_t)tt_ * 128); S = SCQ[tt_]; X = *(const unsigned*)(X2Bw + (size_t)tt_ * DM + 128 * hs + 16 * seg + 2 * r); } while (0)
; #define P7C_ISSUE(G, R0, R1) do { __builtin_amdgcn_s_setprio(3); _Pragma("unroll") for (int i_ = 0; i_ < 16; ++i_) { const unsigned e_ = P7_EID(R0, R1, i_); G[i_] = *(const v4u*)(Vb + (size_t)e_ * 128); } __builtin_amdgcn_s_setprio(0); } while (0)
; __device__ __forceinline__ void p7c_vaxpy(Frame& F, unsigned* bar, unsigned x, unsigned rank) {
;     ...
;     for (int pass = 0; pass < 16; ++pass) {
;         const int hs = (2 * (int)so.vx + pass) & 15; if ((unsigned)(hs >> 1) % so.npop != so.vx) continue;
;         const unsigned char* Vb = F.ws + WS_V + (size_t)hs * (16384 * 128) + 16 * seg;
;         const unsigned char* rp0 = RE16b + r * 32; const unsigned char* cp0 = CQb + r * 16;
;     ...
;         v4u GA[16], GB[16], ra0, ra1, ca, rb0, rb1, cb, cA, cB; float sa, sb, sA, sB; unsigned xa, xb2, xA, xB;
;         P7C_LOADA(ra0, ra1, ca, sa, xa, gwl);
;         P7C_LOADA(rb0, rb1, cb, sb, xb2, gwl + stride);
;         P7C_ISSUE(GA, ra0, ra1); cA = ca; sA = sa; xA = xa;
.LBB0_1084:
	s_waitcnt vmcnt(23)
	v_add_u32_e32 v0, s22, v192
	v_bfe_u32 v1, v0, 1, 3
	v_mul_hi_u32 v2, v1, v193
	v_mul_lo_u32 v2, v2, v191
	v_sub_u32_e32 v1, v1, v2
	v_sub_u32_e32 v2, v1, v191
	v_cmp_ge_u32_e32 vcc, v1, v191
	s_nop 1
	v_cndmask_b32_e32 v1, v1, v2, vcc
	v_sub_u32_e32 v2, v1, v191
	v_cmp_ge_u32_e32 vcc, v1, v191
	s_nop 1
	v_cndmask_b32_e32 v1, v1, v2, vcc
	v_cmp_ne_u32_e32 vcc, v1, v190
	s_cbranch_vccnz .LBB0_1083
	v_and_b32_e32 v80, 15, v0
	v_lshlrev_b32_e32 v156, 21, v80
	v_lshl_add_u64 v[180:181], v[176:177], 0, v[156:157]
	s_nop 1
	v_readfirstlane_b32 s56, v180
	v_readfirstlane_b32 s57, v181
	s_movk_i32 s58, 0x80
	s_nop 3
	s_sub_u32 s56, s56, 0x80
	s_subb_u32 s57, s57, 0
	s_nop 3
	v_subrev_u32_e32 v200, s56, v180
	v_and_b32_e32 v12, 7, v231
	v_bfe_u32 v13, v231, 4, 1
	v_lshlrev_b32_e32 v14, 4, v12
	v_lshlrev_b32_e32 v13, 2, v13
	v_sub_u32_e32 v14, v200, v14
	v_xor_b32_e32 v12, v12, v13
	v_xor_b32_e32 v13, 1, v12
	v_lshl_add_u32 v201, v13, 4, v14
	v_xor_b32_e32 v13, 2, v12
	v_lshl_add_u32 v202, v13, 4, v14
	v_xor_b32_e32 v13, 3, v12
	v_lshl_add_u32 v203, v13, 4, v14
	v_lshl_add_u32 v200, v12, 4, v14
	v_readfirstlane_b32 s60, v158
	v_readfirstlane_b32 s61, v159
	v_readfirstlane_b32 s82, v160
	v_readfirstlane_b32 s83, v161
	v_readfirstlane_b32 s98, v164
	v_readfirstlane_b32 s99, v165
	v_readfirstlane_b32 s100, v168
	v_readfirstlane_b32 s101, v169
	v_readfirstlane_b32 s28, v170
	v_readfirstlane_b32 s29, v171
	s_lshr_b32 s59, s97, 4
	s_add_i32 s59, s59, 0x21000
	v_lshlrev_b32_e32 v16, 2, v231
	v_lshrrev_b32_e32 v17, 3, v231
	v_lshlrev_b32_e32 v18, 4, v17
	v_and_b32_e32 v18, 0xffffffef, v18
	v_add_u32_e32 v18, s59, v18
	v_lshl_add_u32 v17, v17, 5, s59
	v_lshlrev_b32_e32 v156, 8, v80
	global_load_dwordx4 v[24:27], v[162:163], off offset:16
	global_load_dwordx4 v[8:11], v[162:163], off
	s_waitcnt vmcnt(4)
	v_lshl_add_u64 v[12:13], v[166:167], 0, v[156:157]
	s_add_i32 m0, s59, 0x100
	s_nop 0
	global_load_lds_dword v16, s[98:99]
	s_add_i32 m0, s59, 0x200
	s_nop 0
	global_load_lds_dword v16, s[100:101]
	s_add_i32 m0, s59, 0x300
	s_nop 0
	global_load_lds_dword v16, s[28:29]
	v_lshl_add_u64 v[14:15], v[172:173], 0, v[156:157]
	global_load_dword v196, v157, s[4:5]
	global_load_dword v197, v[12:13], off
	global_load_dword v198, v157, s[6:7]
	global_load_dword v199, v[14:15], off
	s_setprio 3
	s_waitcnt vmcnt(7)
	v_mad_u32_u16 v12, v8, s58, v200 op_sel:[0,0,0,0]
	v_mad_u32_u16 v14, v8, s58, v201 op_sel:[1,0,0,0]
	s_add_i32 m0, s97, 0x0
	s_nop 0
	global_load_lds_dwordx4 v12, s[56:57]
	s_add_i32 m0, s97, 0x400
	s_nop 0
	global_load_lds_dwordx4 v14, s[56:57]
	v_mad_u32_u16 v12, v9, s58, v202 op_sel:[0,0,0,0]
	v_mad_u32_u16 v8, v9, s58, v203 op_sel:[1,0,0,0]
	s_add_i32 m0, s97, 0x800
	s_nop 0
	global_load_lds_dwordx4 v12, s[56:57]
	s_add_i32 m0, s97, 0xc00
	s_nop 0
	global_load_lds_dwordx4 v8, s[56:57]
	v_mad_u32_u16 v8, v10, s58, v200 op_sel:[0,0,0,0]
	v_mad_u32_u16 v12, v10, s58, v201 op_sel:[1,0,0,0]
	s_add_i32 m0, s97, 0x1000
	s_nop 0
	global_load_lds_dwordx4 v8, s[56:57]
	s_add_i32 m0, s97, 0x1400
	s_nop 0
	global_load_lds_dwordx4 v12, s[56:57]
	v_mad_u32_u16 v8, v11, s58, v202 op_sel:[0,0,0,0]
	v_mad_u32_u16 v10, v11, s58, v203 op_sel:[1,0,0,0]
	s_add_i32 m0, s97, 0x1800
	s_nop 0
	global_load_lds_dwordx4 v8, s[56:57]
	s_add_i32 m0, s97, 0x1c00
	s_nop 0
	global_load_lds_dwordx4 v10, s[56:57]
	v_mad_u32_u16 v8, v24, s58, v200 op_sel:[0,0,0,0]
	v_mad_u32_u16 v10, v24, s58, v201 op_sel:[1,0,0,0]
	s_add_i32 m0, s97, 0x2000
	s_nop 0
	global_load_lds_dwordx4 v8, s[56:57]
	s_add_i32 m0, s97, 0x2400
	s_nop 0
	global_load_lds_dwordx4 v10, s[56:57]
	v_mad_u32_u16 v8, v25, s58, v202 op_sel:[0,0,0,0]
	v_mad_u32_u16 v10, v25, s58, v203 op_sel:[1,0,0,0]
	s_add_i32 m0, s97, 0x2800
	s_nop 0
	global_load_lds_dwordx4 v8, s[56:57]
	s_add_i32 m0, s97, 0x2c00
	s_nop 0
	global_load_lds_dwordx4 v10, s[56:57]
	v_mad_u32_u16 v8, v26, s58, v200 op_sel:[0,0,0,0]
	v_mad_u32_u16 v12, v26, s58, v201 op_sel:[1,0,0,0]
	v_mad_u32_u16 v24, v27, s58, v202 op_sel:[0,0,0,0]
	v_mad_u32_u16 v28, v27, s58, v203 op_sel:[1,0,0,0]
	s_add_i32 m0, s97, 0x3000
	s_nop 0
	global_load_lds_dwordx4 v8, s[56:57]
	s_nop 0
	s_add_i32 m0, s97, 0x3400
	s_nop 0
	global_load_lds_dwordx4 v12, s[56:57]
	s_nop 0
	s_add_i32 m0, s97, 0x3800
	s_nop 0
	global_load_lds_dwordx4 v24, s[56:57]
	s_nop 0
	s_add_i32 m0, s97, 0x3c00
	s_nop 0
	global_load_lds_dwordx4 v28, s[56:57]
	s_setprio 0
	s_andn2_b64 vcc, exec, s[8:9]
	s_cbranch_vccnz .LBB0_1083
	v_lshlrev_b32_e32 v81, 7, v80
	v_lshlrev_b32_e32 v156, 1, v81
	v_lshl_add_u64 v[182:183], v[174:175], 0, v[156:157]
	v_lshlrev_b32_e32 v156, 2, v80
	v_and_b32_e32 v80, 15, v195
	v_lshl_add_u64 v[184:185], s[2:3], 0, v[156:157]
	v_lshlrev_b32_e32 v156, 2, v80
	v_lshl_add_u64 v[186:187], s[12:13], 0, v[156:157]
	v_lshlrev_b32_e32 v156, 8, v80
	v_lshl_add_u64 v[188:189], v[178:179], 0, v[156:157]
	s_mov_b32 s20, s0
	s_mov_b32 s98, 0x7fffffff
	s_branch .LBB0_1089

; #define P7C_LOADA(R0, R1, C, S, X, t) do { const int tt_ = (t) < NT_TOK ? (t) : NT_TOK - 1; const unsigned char* rp_ = rp0 + (size_t)tt_ * 256; R0 = *(const v4u*)rp_; R1 = *(const v4u*)(rp_ + 16); \
;             C = *(const v4u*)(cp0 + (size_t)tt_ * 128); S = SCQ[tt_]; X = *(const unsigned*)(X2Bw + (size_t)tt_ * DM + 128 * hs + 16 * seg + 2 * r); } while (0)
; #define P7C_ISSUE(G, R0, R1) do { __builtin_amdgcn_s_setprio(3); _Pragma("unroll") for (int i_ = 0; i_ < 16; ++i_) { const unsigned e_ = P7_EID(R0, R1, i_); G[i_] = *(const v4u*)(Vb + (size_t)e_ * 128); } __builtin_amdgcn_s_setprio(0); } while (0)
; __device__ __forceinline__ void p7c_vaxpy(Frame& F, unsigned* bar, unsigned x, unsigned rank) {
;     ...
;         for (int t = gwl; t < NT_TOK; t += 2 * stride) {
;             P7C_LOADA(ra0, ra1, ca, sa, xa, t + 2 * stride); P7C_ISSUE(GB, rb0, rb1); cB = cb; sB = sb; xB = xb2; P7C_COMP(GA, cA, sA, xA, t);
;             P7C_LOADA(rb0, rb1, cb, sb, xb2, t + 3 * stride); P7C_ISSUE(GA, ra0, ra1); cA = ca; sA = sa; xA = xa; P7C_COMP(GB, cB, sB, xB, t + stride);
.LBB0_1089:
	s_add_i32 s27, s20, s10
	s_min_i32 s18, s27, 0x5fff
	s_ashr_i32 s19, s18, 31
	s_waitcnt vmcnt(22)
	ds_read_b128 v[220:223], v18 offset:256
	s_lshl_b64 s[28:29], s[18:19], 8
	ds_read_b128 v[224:227], v18 offset:272
	s_waitcnt lgkmcnt(0)
	s_add_i32 m0, s59, 0x0
	s_add_u32 s28, s28, s60
	s_addc_u32 s29, s29, s61
	global_load_lds_dword v16, s[28:29]
	s_lshl_b64 s[28:29], s[18:19], 7
	s_add_i32 m0, s59, 0x100
	s_add_u32 s28, s28, s82
	s_addc_u32 s29, s29, s83
	global_load_lds_dword v16, s[28:29]
	s_lshl_b64 s[28:29], s[18:19], 2
	s_add_u32 s28, s54, s28
	s_addc_u32 s29, s55, s29
	s_lshl_b64 s[18:19], s[18:19], 12
	s_waitcnt vmcnt(20)
	v_mov_b32_e32 v206, v197
	v_mov_b32_e32 v207, v196
	v_lshl_add_u64 v[80:81], v[182:183], 0, s[18:19]
	s_nop 0
	global_load_dword v196, v157, s[28:29]
	global_load_dword v197, v[80:81], off
	s_waitcnt vmcnt(16)
	ds_read_b128 v[76:79], v17 offset:512
	ds_read_b128 v[64:67], v17 offset:528
	ds_read_b64_tr_b8 v[240:241], v212
	ds_read_b64_tr_b8 v[242:243], v213
	ds_read_b64_tr_b8 v[244:245], v214
	ds_read_b64_tr_b8 v[246:247], v215
	ds_read_b64_tr_b8 v[248:249], v216
	ds_read_b64_tr_b8 v[250:251], v217
	ds_read_b64_tr_b8 v[252:253], v218
	ds_read_b64_tr_b8 v[228:229], v219
	s_waitcnt lgkmcnt(4)
	s_waitcnt vmcnt(12)
	ds_read_b64_tr_b8 v[48:49], v212 offset:4096
	ds_read_b64_tr_b8 v[50:51], v213 offset:4096
	ds_read_b64_tr_b8 v[52:53], v214 offset:4096
	ds_read_b64_tr_b8 v[54:55], v215 offset:4096
	v_dot4_i32_i8 v232, v240, v220, 0
	v_dot4_i32_i8 v233, v242, v220, 0
	v_dot4_i32_i8 v234, v244, v220, 0
	v_dot4_i32_i8 v235, v246, v220, 0
	v_dot4_i32_i8 v232, v241, v224, v232
	v_dot4_i32_i8 v233, v243, v224, v233
	v_dot4_i32_i8 v234, v245, v224, v234
	v_dot4_i32_i8 v235, v247, v224, v235
	s_waitcnt lgkmcnt(4)
	s_setprio 3
	v_permlane32_swap_b32_e32 v104, v108
	v_mad_u32_u16 v80, v76, s58, v200 op_sel:[0,0,0,0]
	v_permlane32_swap_b32_e32 v105, v109
	v_mad_u32_u16 v82, v76, s58, v201 op_sel:[1,0,0,0]
	v_permlane32_swap_b32_e32 v106, v110
	s_add_i32 m0, s97, 0x0
	v_permlane32_swap_b32_e32 v107, v111
	s_nop 0
	v_add_u32_e32 v104, v104, v108
	global_load_lds_dwordx4 v80, s[56:57]
	v_add_u32_e32 v105, v105, v109
	s_add_i32 m0, s97, 0x400
	v_add_u32_e32 v106, v106, v110
	s_nop 0
	v_add_u32_e32 v107, v107, v111
	global_load_lds_dwordx4 v82, s[56:57]
	s_nop 1
	v_mad_u32_u16 v80, v77, s58, v202 op_sel:[0,0,0,0]
	v_permlane16_swap_b32_e32 v104, v106
	v_mad_u32_u16 v76, v77, s58, v203 op_sel:[1,0,0,0]
	v_permlane16_swap_b32_e32 v105, v107
	s_add_i32 m0, s97, 0x800
	v_add_u32_e32 v104, v104, v106
	s_nop 0
	v_add_u32_e32 v105, v105, v107
	global_load_lds_dwordx4 v80, s[56:57]
	s_nop 1
	s_add_i32 m0, s97, 0xc00
	v_mov_b32_dpp v106, v104 quad_perm:[1,0,3,2] row_mask:0xf bank_mask:0xf
	s_nop 0
	v_mov_b32_dpp v107, v105 quad_perm:[1,0,3,2] row_mask:0xf bank_mask:0xf
	global_load_lds_dwordx4 v76, s[56:57]
	s_setprio 0
	ds_read_b64_tr_b8 v[240:241], v216 offset:4096
	ds_read_b64_tr_b8 v[242:243], v217 offset:4096
	ds_read_b64_tr_b8 v[244:245], v218 offset:4096
	ds_read_b64_tr_b8 v[246:247], v219 offset:4096
	v_dot4_i32_i8 v236, v248, v220, 0
	v_dot4_i32_i8 v237, v250, v220, 0
	v_dot4_i32_i8 v238, v252, v220, 0
	v_dot4_i32_i8 v239, v228, v220, 0
	v_dot4_i32_i8 v236, v249, v224, v236
	v_dot4_i32_i8 v237, v251, v224, v237
	v_dot4_i32_i8 v238, v253, v224, v238
	v_dot4_i32_i8 v239, v229, v224, v239
	s_waitcnt lgkmcnt(4)
	s_waitcnt vmcnt(12)
	ds_read_b64_tr_b8 v[248:249], v212 offset:8192
	ds_read_b64_tr_b8 v[250:251], v213 offset:8192
	ds_read_b64_tr_b8 v[252:253], v214 offset:8192
	ds_read_b64_tr_b8 v[228:229], v215 offset:8192
	v_dot4_i32_i8 v232, v48, v221, v232
	v_dot4_i32_i8 v233, v50, v221, v233
	v_dot4_i32_i8 v234, v52, v221, v234
	v_dot4_i32_i8 v235, v54, v221, v235
	v_dot4_i32_i8 v232, v49, v225, v232
	v_dot4_i32_i8 v233, v51, v225, v233
	v_dot4_i32_i8 v234, v53, v225, v234
	v_dot4_i32_i8 v235, v55, v225, v235
	s_waitcnt lgkmcnt(4)
	s_setprio 3
	v_cndmask_b32_e64 v108, v107, v104, s[44:45]
	v_mad_u32_u16 v76, v78, s58, v200 op_sel:[0,0,0,0]
	v_cndmask_b32_e64 v109, v105, v106, s[44:45]
	v_mad_u32_u16 v80, v78, s58, v201 op_sel:[1,0,0,0]
	v_cvt_f32_i32_e32 v108, v108
	s_add_i32 m0, s97, 0x1000
	v_cvt_f32_i32_e32 v109, v109
	s_nop 0
	v_lshlrev_b32_e32 v110, 16, v204
	global_load_lds_dwordx4 v76, s[56:57]
	v_and_b32_e32 v111, 0xffff0000, v204
	s_add_i32 m0, s97, 0x1400
	v_fmac_f32_e32 v110, v205, v108
	s_nop 0
	v_fmac_f32_e32 v111, v205, v109
	global_load_lds_dwordx4 v80, s[56:57]
	v_mul_f32_e32 v115, v111, v111
	v_mad_u32_u16 v76, v79, s58, v202 op_sel:[0,0,0,0]
	v_fmac_f32_e32 v115, v110, v110
	v_mad_u32_u16 v78, v79, s58, v203 op_sel:[1,0,0,0]
	v_cvt_pk_bf16_f32 v117, v110, v111
	s_add_i32 m0, s97, 0x1800
	s_cmpk_gt_i32 s98, 0x5fff
	s_cbranch_scc1 .Lp7c_sk1_b
	s_ashr_i32 s99, s98, 31
	s_lshl_b64 s[100:101], s[98:99], 12
	v_lshl_add_u64 v[118:119], v[182:183], 0, s[100:101]
	global_store_dword v[118:119], v117, off
; #define P7C_LOADA(R0, R1, C, S, X, t) do { const int tt_ = (t) < NT_TOK ? (t) : NT_TOK - 1; const unsigned char* rp_ = rp0 + (size_t)tt_ * 256; R0 = *(const v4u*)rp_; R1 = *(const v4u*)(rp_ + 16); \
;             C = *(const v4u*)(cp0 + (size_t)tt_ * 128); S = SCQ[tt_]; X = *(const unsigned*)(X2Bw + (size_t)tt_ * DM + 128 * hs + 16 * seg + 2 * r); } while (0)
; #define P7C_ISSUE(G, R0, R1) do { __builtin_amdgcn_s_setprio(3); _Pragma("unroll") for (int i_ = 0; i_ < 16; ++i_) { const unsigned e_ = P7_EID(R0, R1, i_); G[i_] = *(const v4u*)(Vb + (size_t)e_ * 128); } __builtin_amdgcn_s_setprio(0); } while (0)
; __device__ __forceinline__ void p7c_vaxpy(Frame& F, unsigned* bar, unsigned x, unsigned rank) {
;     ...
;         for (int t = gwl; t < NT_TOK; t += 2 * stride) {
;             P7C_LOADA(ra0, ra1, ca, sa, xa, t + 2 * stride); P7C_ISSUE(GB, rb0, rb1); cB = cb; sB = sb; xB = xb2; P7C_COMP(GA, cA, sA, xA, t);
;             P7C_LOADA(rb0, rb1, cb, sb, xb2, t + 3 * stride); P7C_ISSUE(GA, ra0, ra1); cA = ca; sA = sa; xA = xa; P7C_COMP(GB, cB, sB, xB, t + stride);
.Lp7c_sk1_b:
	s_nop 0
	s_nop 1
	global_load_lds_dwordx4 v76, s[56:57]
	v_add_f32_dpp v115, v115, v115 quad_perm:[1,0,3,2] row_mask:0xf bank_mask:0xf
	s_add_i32 m0, s97, 0x1c00
	s_nop 1
	s_nop 0
	v_add_f32_dpp v115, v115, v115 quad_perm:[2,3,0,1] row_mask:0xf bank_mask:0xf
	global_load_lds_dwordx4 v78, s[56:57]
	s_setprio 0
	ds_read_b64_tr_b8 v[48:49], v216 offset:8192
	ds_read_b64_tr_b8 v[50:51], v217 offset:8192
	ds_read_b64_tr_b8 v[52:53], v218 offset:8192
	ds_read_b64_tr_b8 v[54:55], v219 offset:8192
	v_dot4_i32_i8 v236, v240, v221, v236
	v_dot4_i32_i8 v237, v242, v221, v237
	v_dot4_i32_i8 v238, v244, v221, v238
	v_dot4_i32_i8 v239, v246, v221, v239
	v_dot4_i32_i8 v236, v241, v225, v236
	v_dot4_i32_i8 v237, v243, v225, v237
	v_dot4_i32_i8 v238, v245, v225, v238
	v_dot4_i32_i8 v239, v247, v225, v239
	s_waitcnt lgkmcnt(4)
	s_waitcnt vmcnt(12)
	ds_read_b64_tr_b8 v[240:241], v212 offset:12288
	ds_read_b64_tr_b8 v[242:243], v213 offset:12288
	ds_read_b64_tr_b8 v[244:245], v214 offset:12288
	ds_read_b64_tr_b8 v[246:247], v215 offset:12288
	v_dot4_i32_i8 v232, v248, v222, v232
	v_dot4_i32_i8 v233, v250, v222, v233
	v_dot4_i32_i8 v234, v252, v222, v234
	v_dot4_i32_i8 v235, v228, v222, v235
	v_dot4_i32_i8 v232, v249, v226, v232
	v_dot4_i32_i8 v233, v251, v226, v233
	v_dot4_i32_i8 v234, v253, v226, v234
	v_dot4_i32_i8 v235, v229, v226, v235
	s_waitcnt lgkmcnt(4)
	s_setprio 3
	s_nop 1
	v_mad_u32_u16 v76, v64, s58, v200 op_sel:[0,0,0,0]
	v_add_f32_dpp v115, v115, v115 row_half_mirror row_mask:0xf bank_mask:0xf
	v_mad_u32_u16 v78, v64, s58, v201 op_sel:[1,0,0,0]
	s_nop 1
	s_add_i32 m0, s97, 0x2000
	v_add_f32_dpp v115, v115, v115 row_mirror row_mask:0xf bank_mask:0xf
	s_nop 0
	v_mov_b32_e32 v116, v115
	global_load_lds_dwordx4 v76, s[56:57]
	s_nop 1
	s_add_i32 m0, s97, 0x2400
	v_permlane16_swap_b32_e32 v115, v116
	s_nop 0
	v_add_f32_e32 v115, v115, v116
	global_load_lds_dwordx4 v78, s[56:57]
	v_mov_b32_e32 v116, v115
	v_mad_u32_u16 v76, v65, s58, v202 op_sel:[0,0,0,0]
	s_nop 1
	v_mad_u32_u16 v64, v65, s58, v203 op_sel:[1,0,0,0]
	v_permlane32_swap_b32_e32 v115, v116
	s_add_i32 m0, s97, 0x2800
	v_add_f32_e32 v115, v115, v116
	s_nop 0
	s_cmpk_gt_i32 s98, 0x5fff
	s_cbranch_scc1 .Lp7c_sk2_b
	s_ashr_i32 s99, s98, 31
	s_lshl_b64 s[100:101], s[98:99], 6
	v_lshl_add_u64 v[118:119], v[184:185], 0, s[100:101]
	s_and_saveexec_b64 s[18:19], s[42:43]
	global_store_dword v[118:119], v115, off
	s_mov_b64 exec, s[18:19]
.Lp7c_sk2_b:
	global_load_lds_dwordx4 v76, s[56:57]
	s_add_i32 m0, s97, 0x2c00
	s_nop 0
	global_load_lds_dwordx4 v64, s[56:57]
	s_setprio 0
	ds_read_b64_tr_b8 v[248:249], v216 offset:12288
	ds_read_b64_tr_b8 v[250:251], v217 offset:12288
	ds_read_b64_tr_b8 v[252:253], v218 offset:12288
	ds_read_b64_tr_b8 v[228:229], v219 offset:12288
	v_dot4_i32_i8 v236, v48, v222, v236
	v_dot4_i32_i8 v237, v50, v222, v237
	v_dot4_i32_i8 v238, v52, v222, v238
	v_dot4_i32_i8 v239, v54, v222, v239
	v_dot4_i32_i8 v236, v49, v226, v236
	v_dot4_i32_i8 v237, v51, v226, v237
	v_dot4_i32_i8 v238, v53, v226, v238
	v_dot4_i32_i8 v239, v55, v226, v239
	s_waitcnt lgkmcnt(4)
	v_dot4_i32_i8 v232, v240, v223, v232
	v_dot4_i32_i8 v233, v242, v223, v233
	v_dot4_i32_i8 v234, v244, v223, v234
	v_dot4_i32_i8 v235, v246, v223, v235
	v_dot4_i32_i8 v232, v241, v227, v232
	v_dot4_i32_i8 v233, v243, v227, v233
	v_dot4_i32_i8 v234, v245, v227, v234
	v_dot4_i32_i8 v235, v247, v227, v235
	s_waitcnt lgkmcnt(0)
	s_setprio 3
	v_mad_u32_u16 v64, v66, s58, v200 op_sel:[0,0,0,0]
	v_mad_u32_u16 v76, v66, s58, v201 op_sel:[1,0,0,0]
	s_add_i32 m0, s97, 0x3000
	s_nop 0
	global_load_lds_dwordx4 v64, s[56:57]
	s_add_i32 m0, s97, 0x3400
	s_nop 0
	global_load_lds_dwordx4 v76, s[56:57]
	v_mad_u32_u16 v64, v67, s58, v202 op_sel:[0,0,0,0]
	v_mad_u32_u16 v66, v67, s58, v203 op_sel:[1,0,0,0]
	s_add_i32 m0, s97, 0x3800
	s_nop 0
	global_load_lds_dwordx4 v64, s[56:57]
	s_add_i32 m0, s97, 0x3c00
	s_nop 0
	global_load_lds_dwordx4 v66, s[56:57]
	s_setprio 0
	v_dot4_i32_i8 v236, v248, v223, v236
	v_dot4_i32_i8 v237, v250, v223, v237
	v_dot4_i32_i8 v238, v252, v223, v238
	v_dot4_i32_i8 v239, v228, v223, v239
	v_dot4_i32_i8 v236, v249, v227, v236
	v_dot4_i32_i8 v237, v251, v227, v237
	v_dot4_i32_i8 v238, v253, v227, v238
	v_dot4_i32_i8 v239, v229, v227, v239
	v_mov_b32_e32 v204, v206
	v_mov_b32_e32 v205, v207
	s_add_i32 s18, s24, s20
	s_min_i32 s18, s18, 0x5fff
	s_ashr_i32 s19, s18, 31
	s_lshl_b64 s[28:29], s[18:19], 8
	s_waitcnt lgkmcnt(0)
	s_waitcnt vmcnt(24)
	ds_read_b128 v[220:223], v18 offset:768
	ds_read_b128 v[224:227], v18 offset:784
	s_waitcnt lgkmcnt(0)
	s_add_i32 m0, s59, 0x200
	s_add_u32 s28, s28, s60
	s_addc_u32 s29, s29, s61
	global_load_lds_dword v16, s[28:29]
	s_lshl_b64 s[28:29], s[18:19], 7
	s_add_i32 m0, s59, 0x300
	s_add_u32 s28, s28, s82
	s_addc_u32 s29, s29, s83
	global_load_lds_dword v16, s[28:29]
	s_lshl_b64 s[28:29], s[18:19], 2
	s_add_u32 s28, s54, s28
	s_addc_u32 s29, s55, s29
	s_lshl_b64 s[18:19], s[18:19], 12
	v_lshl_add_u64 v[10:11], v[182:183], 0, s[18:19]
	global_load_dword v207, v157, s[28:29]
	global_load_dword v206, v[10:11], off
	s_waitcnt vmcnt(16)
	ds_read_b128 v[148:151], v17
	ds_read_b128 v[144:147], v17 offset:16
	ds_read_b64_tr_b8 v[240:241], v212
	ds_read_b64_tr_b8 v[242:243], v213
	ds_read_b64_tr_b8 v[244:245], v214
	ds_read_b64_tr_b8 v[246:247], v215
	ds_read_b64_tr_b8 v[248:249], v216
	ds_read_b64_tr_b8 v[250:251], v217
	ds_read_b64_tr_b8 v[252:253], v218
	ds_read_b64_tr_b8 v[228:229], v219
	s_waitcnt lgkmcnt(4)
	s_waitcnt vmcnt(12)
; #define P7C_LOADA(R0, R1, C, S, X, t) do { const int tt_ = (t) < NT_TOK ? (t) : NT_TOK - 1; const unsigned char* rp_ = rp0 + (size_t)tt_ * 256; R0 = *(const v4u*)rp_; R1 = *(const v4u*)(rp_ + 16); \
;             C = *(const v4u*)(cp0 + (size_t)tt_ * 128); S = SCQ[tt_]; X = *(const unsigned*)(X2Bw + (size_t)tt_ * DM + 128 * hs + 16 * seg + 2 * r); } while (0)
; #define P7C_ISSUE(G, R0, R1) do { __builtin_amdgcn_s_setprio(3); _Pragma("unroll") for (int i_ = 0; i_ < 16; ++i_) { const unsigned e_ = P7_EID(R0, R1, i_); G[i_] = *(const v4u*)(Vb + (size_t)e_ * 128); } __builtin_amdgcn_s_setprio(0); } while (0)
; __device__ __forceinline__ void p7c_vaxpy(Frame& F, unsigned* bar, unsigned x, unsigned rank) {
;     ...
;         for (int t = gwl; t < NT_TOK; t += 2 * stride) {
;             P7C_LOADA(ra0, ra1, ca, sa, xa, t + 2 * stride); P7C_ISSUE(GB, rb0, rb1); cB = cb; sB = sb; xB = xb2; P7C_COMP(GA, cA, sA, xA, t);
;             P7C_LOADA(rb0, rb1, cb, sb, xb2, t + 3 * stride); P7C_ISSUE(GA, ra0, ra1); cA = ca; sA = sa; xA = xa; P7C_COMP(GB, cB, sB, xB, t + stride);
	ds_read_b64_tr_b8 v[128:129], v212 offset:4096
	ds_read_b64_tr_b8 v[130:131], v213 offset:4096
	ds_read_b64_tr_b8 v[132:133], v214 offset:4096
	ds_read_b64_tr_b8 v[134:135], v215 offset:4096
	v_dot4_i32_i8 v104, v240, v220, 0
	v_dot4_i32_i8 v105, v242, v220, 0
	v_dot4_i32_i8 v106, v244, v220, 0
	v_dot4_i32_i8 v107, v246, v220, 0
	v_dot4_i32_i8 v104, v241, v224, v104
	v_dot4_i32_i8 v105, v243, v224, v105
	v_dot4_i32_i8 v106, v245, v224, v106
	v_dot4_i32_i8 v107, v247, v224, v107
	s_waitcnt lgkmcnt(4)
	s_setprio 3
	v_permlane32_swap_b32_e32 v232, v236
	v_mad_u32_u16 v8, v148, s58, v200 op_sel:[0,0,0,0]
	v_permlane32_swap_b32_e32 v233, v237
	v_mad_u32_u16 v10, v148, s58, v201 op_sel:[1,0,0,0]
	v_permlane32_swap_b32_e32 v234, v238
	s_add_i32 m0, s97, 0x0
	v_permlane32_swap_b32_e32 v235, v239
	s_nop 0
	v_add_u32_e32 v232, v232, v236
	global_load_lds_dwordx4 v8, s[56:57]
	v_add_u32_e32 v233, v233, v237
	s_add_i32 m0, s97, 0x400
	v_add_u32_e32 v234, v234, v238
	s_nop 0
	v_add_u32_e32 v235, v235, v239
	global_load_lds_dwordx4 v10, s[56:57]
	s_nop 1
	v_mad_u32_u16 v8, v149, s58, v202 op_sel:[0,0,0,0]
	v_permlane16_swap_b32_e32 v232, v234
	v_mad_u32_u16 v10, v149, s58, v203 op_sel:[1,0,0,0]
	v_permlane16_swap_b32_e32 v233, v235
	s_add_i32 m0, s97, 0x800
	v_add_u32_e32 v232, v232, v234
	s_nop 0
	v_add_u32_e32 v233, v233, v235
	global_load_lds_dwordx4 v8, s[56:57]
	s_nop 1
	s_add_i32 m0, s97, 0xc00
	v_mov_b32_dpp v234, v232 quad_perm:[1,0,3,2] row_mask:0xf bank_mask:0xf
	s_nop 0
	v_mov_b32_dpp v235, v233 quad_perm:[1,0,3,2] row_mask:0xf bank_mask:0xf
	global_load_lds_dwordx4 v10, s[56:57]
	s_setprio 0
	ds_read_b64_tr_b8 v[240:241], v216 offset:4096
	ds_read_b64_tr_b8 v[242:243], v217 offset:4096
	ds_read_b64_tr_b8 v[244:245], v218 offset:4096
	ds_read_b64_tr_b8 v[246:247], v219 offset:4096
	v_dot4_i32_i8 v108, v248, v220, 0
	v_dot4_i32_i8 v109, v250, v220, 0
	v_dot4_i32_i8 v110, v252, v220, 0
	v_dot4_i32_i8 v111, v228, v220, 0
	v_dot4_i32_i8 v108, v249, v224, v108
	v_dot4_i32_i8 v109, v251, v224, v109
	v_dot4_i32_i8 v110, v253, v224, v110
	v_dot4_i32_i8 v111, v229, v224, v111
	s_waitcnt lgkmcnt(4)
	s_waitcnt vmcnt(12)
	ds_read_b64_tr_b8 v[248:249], v212 offset:8192
	ds_read_b64_tr_b8 v[250:251], v213 offset:8192
	ds_read_b64_tr_b8 v[252:253], v214 offset:8192
	ds_read_b64_tr_b8 v[228:229], v215 offset:8192
	v_dot4_i32_i8 v104, v128, v221, v104
	v_dot4_i32_i8 v105, v130, v221, v105
	v_dot4_i32_i8 v106, v132, v221, v106
	v_dot4_i32_i8 v107, v134, v221, v107
	v_dot4_i32_i8 v104, v129, v225, v104
	v_dot4_i32_i8 v105, v131, v225, v105
	v_dot4_i32_i8 v106, v133, v225, v106
	v_dot4_i32_i8 v107, v135, v225, v107
	s_waitcnt lgkmcnt(4)
	s_setprio 3
	v_cndmask_b32_e64 v236, v235, v232, s[44:45]
	v_mad_u32_u16 v8, v150, s58, v200 op_sel:[0,0,0,0]
	v_cndmask_b32_e64 v237, v233, v234, s[44:45]
	v_mad_u32_u16 v10, v150, s58, v201 op_sel:[1,0,0,0]
	v_cvt_f32_i32_e32 v236, v236
	s_add_i32 m0, s97, 0x1000
	v_cvt_f32_i32_e32 v237, v237
	s_nop 0
	v_lshlrev_b32_e32 v238, 16, v204
	global_load_lds_dwordx4 v8, s[56:57]
	v_and_b32_e32 v239, 0xffff0000, v204
	s_add_i32 m0, s97, 0x1400
	v_fmac_f32_e32 v238, v205, v236
	s_nop 0
	v_fmac_f32_e32 v239, v205, v237
	global_load_lds_dwordx4 v10, s[56:57]
	v_mul_f32_e32 v112, v239, v239
	v_mad_u32_u16 v8, v151, s58, v202 op_sel:[0,0,0,0]
	v_fmac_f32_e32 v112, v238, v238
	v_mad_u32_u16 v10, v151, s58, v203 op_sel:[1,0,0,0]
	v_cvt_pk_bf16_f32 v114, v238, v239
	s_add_i32 m0, s97, 0x1800
	global_store_dword v[188:189], v114, off
	s_nop 0
	s_nop 1
	global_load_lds_dwordx4 v8, s[56:57]
	v_add_f32_dpp v112, v112, v112 quad_perm:[1,0,3,2] row_mask:0xf bank_mask:0xf
	s_add_i32 m0, s97, 0x1c00
	s_nop 1
	s_nop 0
	v_add_f32_dpp v112, v112, v112 quad_perm:[2,3,0,1] row_mask:0xf bank_mask:0xf
	global_load_lds_dwordx4 v10, s[56:57]
	s_setprio 0
	ds_read_b64_tr_b8 v[128:129], v216 offset:8192
	ds_read_b64_tr_b8 v[130:131], v217 offset:8192
	ds_read_b64_tr_b8 v[132:133], v218 offset:8192
	ds_read_b64_tr_b8 v[134:135], v219 offset:8192
	v_dot4_i32_i8 v108, v240, v221, v108
	v_dot4_i32_i8 v109, v242, v221, v109
	v_dot4_i32_i8 v110, v244, v221, v110
	v_dot4_i32_i8 v111, v246, v221, v111
	v_dot4_i32_i8 v108, v241, v225, v108
	v_dot4_i32_i8 v109, v243, v225, v109
	v_dot4_i32_i8 v110, v245, v225, v110
	v_dot4_i32_i8 v111, v247, v225, v111
	s_waitcnt lgkmcnt(4)
	s_waitcnt vmcnt(12)
	ds_read_b64_tr_b8 v[240:241], v212 offset:12288
	ds_read_b64_tr_b8 v[242:243], v213 offset:12288
	ds_read_b64_tr_b8 v[244:245], v214 offset:12288
	ds_read_b64_tr_b8 v[246:247], v215 offset:12288
	v_dot4_i32_i8 v104, v248, v222, v104
	v_dot4_i32_i8 v105, v250, v222, v105
	v_dot4_i32_i8 v106, v252, v222, v106
	v_dot4_i32_i8 v107, v228, v222, v107
	v_dot4_i32_i8 v104, v249, v226, v104
	v_dot4_i32_i8 v105, v251, v226, v105
	v_dot4_i32_i8 v106, v253, v226, v106
	v_dot4_i32_i8 v107, v229, v226, v107
	s_waitcnt lgkmcnt(4)
; #define P7C_LOADA(R0, R1, C, S, X, t) do { const int tt_ = (t) < NT_TOK ? (t) : NT_TOK - 1; const unsigned char* rp_ = rp0 + (size_t)tt_ * 256; R0 = *(const v4u*)rp_; R1 = *(const v4u*)(rp_ + 16); \
;             C = *(const v4u*)(cp0 + (size_t)tt_ * 128); S = SCQ[tt_]; X = *(const unsigned*)(X2Bw + (size_t)tt_ * DM + 128 * hs + 16 * seg + 2 * r); } while (0)
; #define P7C_ISSUE(G, R0, R1) do { __builtin_amdgcn_s_setprio(3); _Pragma("unroll") for (int i_ = 0; i_ < 16; ++i_) { const unsigned e_ = P7_EID(R0, R1, i_); G[i_] = *(const v4u*)(Vb + (size_t)e_ * 128); } __builtin_amdgcn_s_setprio(0); } while (0)
; __device__ __forceinline__ void p7c_vaxpy(Frame& F, unsigned* bar, unsigned x, unsigned rank) {
;     ...
;         for (int t = gwl; t < NT_TOK; t += 2 * stride) {
;             P7C_LOADA(ra0, ra1, ca, sa, xa, t + 2 * stride); P7C_ISSUE(GB, rb0, rb1); cB = cb; sB = sb; xB = xb2; P7C_COMP(GA, cA, sA, xA, t);
;             P7C_LOADA(rb0, rb1, cb, sb, xb2, t + 3 * stride); P7C_ISSUE(GA, ra0, ra1); cA = ca; sA = sa; xA = xa; P7C_COMP(GB, cB, sB, xB, t + stride);
	s_setprio 3
	s_nop 1
	v_mad_u32_u16 v8, v144, s58, v200 op_sel:[0,0,0,0]
	v_add_f32_dpp v112, v112, v112 row_half_mirror row_mask:0xf bank_mask:0xf
	v_mad_u32_u16 v10, v144, s58, v201 op_sel:[1,0,0,0]
	s_nop 1
	s_add_i32 m0, s97, 0x2000
	v_add_f32_dpp v112, v112, v112 row_mirror row_mask:0xf bank_mask:0xf
	s_nop 0
	v_mov_b32_e32 v113, v112
	global_load_lds_dwordx4 v8, s[56:57]
	s_nop 1
	s_add_i32 m0, s97, 0x2400
	v_permlane16_swap_b32_e32 v112, v113
	s_nop 0
	v_add_f32_e32 v112, v112, v113
	global_load_lds_dwordx4 v10, s[56:57]
	v_mov_b32_e32 v113, v112
	v_mad_u32_u16 v8, v145, s58, v202 op_sel:[0,0,0,0]
	s_nop 1
	v_mad_u32_u16 v10, v145, s58, v203 op_sel:[1,0,0,0]
	v_permlane32_swap_b32_e32 v112, v113
	s_add_i32 m0, s97, 0x2800
	v_add_f32_e32 v112, v112, v113
	s_nop 0
	s_and_saveexec_b64 s[18:19], s[42:43]
	global_store_dword v[186:187], v112, off
	s_mov_b64 exec, s[18:19]
	global_load_lds_dwordx4 v8, s[56:57]
	s_add_i32 m0, s97, 0x2c00
	s_nop 0
	global_load_lds_dwordx4 v10, s[56:57]
	s_setprio 0
	ds_read_b64_tr_b8 v[248:249], v216 offset:12288
	ds_read_b64_tr_b8 v[250:251], v217 offset:12288
	ds_read_b64_tr_b8 v[252:253], v218 offset:12288
	ds_read_b64_tr_b8 v[228:229], v219 offset:12288
	v_dot4_i32_i8 v108, v128, v222, v108
	v_dot4_i32_i8 v109, v130, v222, v109
	v_dot4_i32_i8 v110, v132, v222, v110
	v_dot4_i32_i8 v111, v134, v222, v111
	v_dot4_i32_i8 v108, v129, v226, v108
	v_dot4_i32_i8 v109, v131, v226, v109
	v_dot4_i32_i8 v110, v133, v226, v110
	v_dot4_i32_i8 v111, v135, v226, v111
	s_waitcnt lgkmcnt(4)
	v_dot4_i32_i8 v104, v240, v223, v104
	v_dot4_i32_i8 v105, v242, v223, v105
	v_dot4_i32_i8 v106, v244, v223, v106
	v_dot4_i32_i8 v107, v246, v223, v107
	v_dot4_i32_i8 v104, v241, v227, v104
	v_dot4_i32_i8 v105, v243, v227, v105
	v_dot4_i32_i8 v106, v245, v227, v106
	v_dot4_i32_i8 v107, v247, v227, v107
	s_waitcnt lgkmcnt(0)
	s_setprio 3
	v_mad_u32_u16 v8, v146, s58, v200 op_sel:[0,0,0,0]
	v_mad_u32_u16 v12, v146, s58, v201 op_sel:[1,0,0,0]
	v_mad_u32_u16 v24, v147, s58, v202 op_sel:[0,0,0,0]
	v_mad_u32_u16 v28, v147, s58, v203 op_sel:[1,0,0,0]
	s_add_i32 m0, s97, 0x3000
	s_nop 0
	global_load_lds_dwordx4 v8, s[56:57]
	s_nop 0
	s_add_i32 m0, s97, 0x3400
	s_nop 0
	global_load_lds_dwordx4 v12, s[56:57]
	s_nop 0
	s_add_i32 m0, s97, 0x3800
	s_nop 0
	global_load_lds_dwordx4 v24, s[56:57]
	s_nop 0
	s_add_i32 m0, s97, 0x3c00
	s_nop 0
	global_load_lds_dwordx4 v28, s[56:57]
	s_setprio 0
	v_dot4_i32_i8 v108, v248, v223, v108
	v_dot4_i32_i8 v109, v250, v223, v109
	v_dot4_i32_i8 v110, v252, v223, v110
	v_dot4_i32_i8 v111, v228, v223, v111
	v_dot4_i32_i8 v108, v249, v227, v108
	v_dot4_i32_i8 v109, v251, v227, v109
	v_dot4_i32_i8 v110, v253, v227, v110
	v_dot4_i32_i8 v111, v229, v227, v111
	v_mov_b32_e32 v204, v199
	v_mov_b32_e32 v205, v198
	s_add_i32 s98, s23, s20
	s_branch .LBB0_1088
.Lp7c_drain:
	s_nop 2
	v_permlane32_swap_b32_e32 v104, v108
	v_permlane32_swap_b32_e32 v105, v109
	v_permlane32_swap_b32_e32 v106, v110
	v_permlane32_swap_b32_e32 v107, v111
	v_add_u32_e32 v104, v104, v108
	v_add_u32_e32 v105, v105, v109
	v_add_u32_e32 v106, v106, v110
	v_add_u32_e32 v107, v107, v111
	s_nop 1
	v_permlane16_swap_b32_e32 v104, v106
	v_permlane16_swap_b32_e32 v105, v107
	v_add_u32_e32 v104, v104, v106
	v_add_u32_e32 v105, v105, v107
	s_nop 1
	v_mov_b32_dpp v106, v104 quad_perm:[1,0,3,2] row_mask:0xf bank_mask:0xf
	v_mov_b32_dpp v107, v105 quad_perm:[1,0,3,2] row_mask:0xf bank_mask:0xf
	v_cndmask_b32_e64 v108, v107, v104, s[44:45]
	v_cndmask_b32_e64 v109, v105, v106, s[44:45]
	v_cvt_f32_i32_e32 v108, v108
	v_cvt_f32_i32_e32 v109, v109
	v_lshlrev_b32_e32 v110, 16, v204
	v_and_b32_e32 v111, 0xffff0000, v204
	v_fmac_f32_e32 v110, v205, v108
	v_fmac_f32_e32 v111, v205, v109
	v_mul_f32_e32 v115, v111, v111
	v_fmac_f32_e32 v115, v110, v110
	v_cvt_pk_bf16_f32 v117, v110, v111
	s_cmpk_gt_i32 s98, 0x5fff
	s_cbranch_scc1 .Lp7c_sk1_d
	s_ashr_i32 s99, s98, 31
	s_lshl_b64 s[100:101], s[98:99], 12
	v_lshl_add_u64 v[118:119], v[182:183], 0, s[100:101]
	global_store_dword v[118:119], v117, off
.Lp7c_sk1_d:
	s_nop 1
	v_add_f32_dpp v115, v115, v115 quad_perm:[1,0,3,2] row_mask:0xf bank_mask:0xf
	s_nop 1
	v_add_f32_dpp v115, v115, v115 quad_perm:[2,3,0,1] row_mask:0xf bank_mask:0xf
	s_nop 1
	v_add_f32_dpp v115, v115, v115 row_half_mirror row_mask:0xf bank_mask:0xf
	s_nop 1
	v_add_f32_dpp v115, v115, v115 row_mirror row_mask:0xf bank_mask:0xf
	v_mov_b32_e32 v116, v115
	s_nop 1
	v_permlane16_swap_b32_e32 v115, v116
	v_add_f32_e32 v115, v115, v116
	v_mov_b32_e32 v116, v115
	s_nop 1
	v_permlane32_swap_b32_e32 v115, v116
	v_add_f32_e32 v115, v115, v116
	s_cmpk_gt_i32 s98, 0x5fff
	s_cbranch_scc1 .Lp7c_sk2_d
	s_ashr_i32 s99, s98, 31
	s_lshl_b64 s[100:101], s[98:99], 6
	v_lshl_add_u64 v[118:119], v[184:185], 0, s[100:101]
	s_and_saveexec_b64 s[18:19], s[42:43]
	global_store_dword v[118:119], v115, off
	s_mov_b64 exec, s[18:19]
